# v31: v29 without the s_setprio 0 / s_setprio 1 toggle in the middle of each 32-MFMA segment (priority stays raised for the whole segment) in the three GEMM loops
# speedup vs baseline: 1.0083x; 1.0083x over previous
.LBB0_155:
	s_ashr_i32 s23, s22, 31
	s_lshl_b64 s[8:9], s[22:23], 19
	s_add_u32 s24, s30, s8
	s_addc_u32 s25, s31, s9
	s_and_b64 s[8:9], s[4:5], exec
	s_cselect_b32 s3, s25, s1
	s_cselect_b32 s23, s24, s0
	s_ashr_i32 s21, s20, 31
	s_lshl_b64 s[8:9], s[20:21], 19
	s_add_u32 s26, s34, s8
	s_addc_u32 s27, s35, s9
	s_and_b64 s[8:9], s[4:5], exec
	s_cselect_b32 s21, s27, s7
	s_cselect_b32 s28, s26, s6
	s_add_u32 s0, s0, 0x40080
	s_addc_u32 s1, s1, 0
	s_add_u32 s29, s6, 0x100
	s_addc_u32 s42, s7, 0
	s_mov_b32 s49, -2
	s_add_u32 s6, s0, 0xfffc0080
	s_addc_u32 s7, s1, -1
	s_add_i32 s50, 16, 0x10000
	s_cmp_eq_u32 s49, 12
	s_cselect_b32 s9, s3, s7
	s_cselect_b32 s8, s23, s6
	v_add_u32_e32 v151, s50, v176
	s_cselect_b32 s7, s21, s42
	s_cselect_b32 s6, s28, s29
	s_add_i32 s52, 16, 0x14000
	ds_read_b128 v[132:135], v151
	ds_read_b128 v[152:155], v151 offset:1024
	ds_read_b128 v[156:159], v151 offset:2048
	ds_read_b128 v[160:163], v151 offset:3072
	v_add_u32_e32 v151, s52, v176
	ds_read_b128 v[164:167], v151
	ds_read_b128 v[168:171], v151 offset:1024
	ds_read_b128 v[172:175], v151 offset:2048
	ds_read_b128 v[180:183], v151 offset:3072
	v_lshl_add_u64 v[216:217], s[0:1], 0, v[146:147]
	s_add_i32 m0, s37, 0xc000
	ds_read_b128 v[184:187], v178
	ds_read_b128 v[188:191], v178 offset:1024
	ds_read_b128 v[192:195], v178 offset:2048
	ds_read_b128 v[196:199], v178 offset:3072
	ds_read_b128 v[200:203], v178 offset:4096
	ds_read_b128 v[204:207], v178 offset:5120
	ds_read_b128 v[208:211], v178 offset:6144
	ds_read_b128 v[212:215], v178 offset:7168
	global_load_lds_dwordx4 v[216:217], off
	v_lshl_add_u64 v[216:217], s[0:1], 0, v[148:149]
	s_add_i32 m0, s37, 0xe000
	s_nop 0
	global_load_lds_dwordx4 v[216:217], off
	s_waitcnt vmcnt(8)
	s_waitcnt lgkmcnt(0)
	s_barrier
	s_setprio 1
	s_waitcnt lgkmcnt(0)
	v_mfma_f32_16x16x32_bf16 v[128:131], v[132:135], v[184:187], 0
	v_mfma_f32_16x16x32_bf16 v[124:127], v[156:159], v[184:187], 0
	v_mfma_f32_16x16x32_bf16 v[112:115], v[132:135], v[192:195], 0
	v_mfma_f32_16x16x32_bf16 v[108:111], v[156:159], v[192:195], 0
	v_mfma_f32_16x16x32_bf16 v[96:99], v[132:135], v[200:203], 0
	v_mfma_f32_16x16x32_bf16 v[92:95], v[156:159], v[200:203], 0
	v_mfma_f32_16x16x32_bf16 v[80:83], v[132:135], v[208:211], 0
	v_mfma_f32_16x16x32_bf16 v[76:79], v[156:159], v[208:211], 0
	v_mfma_f32_16x16x32_bf16 v[128:131], v[152:155], v[188:191], v[128:131]
	v_mfma_f32_16x16x32_bf16 v[124:127], v[160:163], v[188:191], v[124:127]
	v_mfma_f32_16x16x32_bf16 v[112:115], v[152:155], v[196:199], v[112:115]
	v_mfma_f32_16x16x32_bf16 v[108:111], v[160:163], v[196:199], v[108:111]
	v_mfma_f32_16x16x32_bf16 v[96:99], v[152:155], v[204:207], v[96:99]
	v_mfma_f32_16x16x32_bf16 v[92:95], v[160:163], v[204:207], v[92:95]
	v_mfma_f32_16x16x32_bf16 v[80:83], v[152:155], v[212:215], v[80:83]
	v_mfma_f32_16x16x32_bf16 v[76:79], v[160:163], v[212:215], v[76:79]
	v_mfma_f32_16x16x32_bf16 v[120:123], v[164:167], v[184:187], 0
	v_mfma_f32_16x16x32_bf16 v[116:119], v[172:175], v[184:187], 0
	v_mfma_f32_16x16x32_bf16 v[104:107], v[164:167], v[192:195], 0
	v_mfma_f32_16x16x32_bf16 v[100:103], v[172:175], v[192:195], 0
	v_mfma_f32_16x16x32_bf16 v[88:91], v[164:167], v[200:203], 0
	v_mfma_f32_16x16x32_bf16 v[84:87], v[172:175], v[200:203], 0
	v_mfma_f32_16x16x32_bf16 v[72:75], v[164:167], v[208:211], 0
	v_mfma_f32_16x16x32_bf16 v[68:71], v[172:175], v[208:211], 0
	v_mfma_f32_16x16x32_bf16 v[120:123], v[168:171], v[188:191], v[120:123]
	v_mfma_f32_16x16x32_bf16 v[116:119], v[180:183], v[188:191], v[116:119]
	v_mfma_f32_16x16x32_bf16 v[104:107], v[168:171], v[196:199], v[104:107]
	v_mfma_f32_16x16x32_bf16 v[100:103], v[180:183], v[196:199], v[100:103]
	v_mfma_f32_16x16x32_bf16 v[88:91], v[168:171], v[204:207], v[88:91]
	v_mfma_f32_16x16x32_bf16 v[84:87], v[180:183], v[204:207], v[84:87]
	v_mfma_f32_16x16x32_bf16 v[72:75], v[168:171], v[212:215], v[72:75]
	v_mfma_f32_16x16x32_bf16 v[68:71], v[180:183], v[212:215], v[68:71]
	s_setprio 0
	s_barrier
	s_add_i32 s50, s50, s36
	v_lshl_add_u64 v[216:217], s[6:7], 0, v[138:139]
	s_mov_b32 m0, s50
	ds_read_b128 v[184:187], v178 offset:16384
	ds_read_b128 v[188:191], v178 offset:17408
	ds_read_b128 v[192:195], v178 offset:18432
	ds_read_b128 v[196:199], v178 offset:19456
	ds_read_b128 v[200:203], v178 offset:20480
	ds_read_b128 v[204:207], v178 offset:21504
	ds_read_b128 v[208:211], v178 offset:22528
	ds_read_b128 v[212:215], v178 offset:23552
	global_load_lds_dwordx4 v[216:217], off
	s_add_i32 m0, s50, 0x2000
	s_add_u32 s50, s6, 0x40000
	v_lshl_add_u64 v[218:219], s[6:7], 0, v[0:1]
	s_addc_u32 s51, s7, 0
	s_add_i32 s52, s52, s36
	global_load_lds_dwordx4 v[218:219], off
	v_lshl_add_u64 v[220:221], s[50:51], 0, v[138:139]
	s_mov_b32 m0, s52
	v_lshl_add_u64 v[224:225], s[8:9], 0, v[136:137]
	global_load_lds_dwordx4 v[220:221], off
	v_lshl_add_u64 v[220:221], s[50:51], 0, v[0:1]
	s_add_i32 m0, s52, 0x2000
	s_nop 0
	global_load_lds_dwordx4 v[220:221], off
	v_lshl_add_u64 v[220:221], s[8:9], 0, v[140:141]
	s_waitcnt vmcnt(6)
	s_waitcnt lgkmcnt(0)
	s_barrier
	s_setprio 1
	s_waitcnt lgkmcnt(0)
	v_mfma_f32_16x16x32_bf16 v[64:67], v[132:135], v[184:187], 0
	v_mfma_f32_16x16x32_bf16 v[60:63], v[156:159], v[184:187], 0
	v_mfma_f32_16x16x32_bf16 v[48:51], v[132:135], v[192:195], 0
	v_mfma_f32_16x16x32_bf16 v[44:47], v[156:159], v[192:195], 0
	v_mfma_f32_16x16x32_bf16 v[32:35], v[132:135], v[200:203], 0
	v_mfma_f32_16x16x32_bf16 v[28:31], v[156:159], v[200:203], 0
	v_mfma_f32_16x16x32_bf16 v[16:19], v[132:135], v[208:211], 0
	v_mfma_f32_16x16x32_bf16 v[12:15], v[156:159], v[208:211], 0
	v_mfma_f32_16x16x32_bf16 v[64:67], v[152:155], v[188:191], v[64:67]
	v_mfma_f32_16x16x32_bf16 v[60:63], v[160:163], v[188:191], v[60:63]
	v_mfma_f32_16x16x32_bf16 v[48:51], v[152:155], v[196:199], v[48:51]
	v_mfma_f32_16x16x32_bf16 v[44:47], v[160:163], v[196:199], v[44:47]
	v_mfma_f32_16x16x32_bf16 v[32:35], v[152:155], v[204:207], v[32:35]
	v_mfma_f32_16x16x32_bf16 v[28:31], v[160:163], v[204:207], v[28:31]
	v_mfma_f32_16x16x32_bf16 v[16:19], v[152:155], v[212:215], v[16:19]
	v_mfma_f32_16x16x32_bf16 v[12:15], v[160:163], v[212:215], v[12:15]
	v_mfma_f32_16x16x32_bf16 v[56:59], v[164:167], v[184:187], 0
	v_mfma_f32_16x16x32_bf16 v[52:55], v[172:175], v[184:187], 0
	v_mfma_f32_16x16x32_bf16 v[40:43], v[164:167], v[192:195], 0
	v_mfma_f32_16x16x32_bf16 v[36:39], v[172:175], v[192:195], 0
	v_mfma_f32_16x16x32_bf16 v[24:27], v[164:167], v[200:203], 0
	v_mfma_f32_16x16x32_bf16 v[20:23], v[172:175], v[200:203], 0
	v_mfma_f32_16x16x32_bf16 v[8:11], v[164:167], v[208:211], 0
	v_mfma_f32_16x16x32_bf16 v[4:7], v[172:175], v[208:211], 0
	v_mfma_f32_16x16x32_bf16 v[56:59], v[168:171], v[188:191], v[56:59]
	v_mfma_f32_16x16x32_bf16 v[52:55], v[180:183], v[188:191], v[52:55]
	v_mfma_f32_16x16x32_bf16 v[40:43], v[168:171], v[196:199], v[40:43]
	v_mfma_f32_16x16x32_bf16 v[36:39], v[180:183], v[196:199], v[36:39]
	v_mfma_f32_16x16x32_bf16 v[24:27], v[168:171], v[204:207], v[24:27]
	v_mfma_f32_16x16x32_bf16 v[20:23], v[180:183], v[204:207], v[20:23]
	v_mfma_f32_16x16x32_bf16 v[8:11], v[168:171], v[212:215], v[8:11]
	v_mfma_f32_16x16x32_bf16 v[4:7], v[180:183], v[212:215], v[4:7]
	s_setprio 0
	s_barrier
	s_branch .Lb1_ph3
.LBB0_156:
	s_add_u32 s6, s0, 0xfffc0080
	s_addc_u32 s7, s1, -1
	s_add_i32 s50, 16, 0x10000
	s_cmp_eq_u32 s49, 12
	s_cselect_b32 s9, s3, s7
	s_cselect_b32 s8, s23, s6
	v_add_u32_e32 v151, s50, v176
	s_cselect_b32 s7, s21, s42
	s_cselect_b32 s6, s28, s29
	s_add_i32 s52, 16, 0x14000
	ds_read_b128 v[132:135], v151
	ds_read_b128 v[152:155], v151 offset:1024
	ds_read_b128 v[156:159], v151 offset:2048
	ds_read_b128 v[160:163], v151 offset:3072
	v_add_u32_e32 v151, s52, v176
	ds_read_b128 v[164:167], v151
	ds_read_b128 v[168:171], v151 offset:1024
	ds_read_b128 v[172:175], v151 offset:2048
	ds_read_b128 v[180:183], v151 offset:3072
	v_lshl_add_u64 v[216:217], s[0:1], 0, v[146:147]
	s_add_i32 m0, s37, 0xc000
	ds_read_b128 v[184:187], v178
	ds_read_b128 v[188:191], v178 offset:1024
	ds_read_b128 v[192:195], v178 offset:2048
	ds_read_b128 v[196:199], v178 offset:3072
	ds_read_b128 v[200:203], v178 offset:4096
	ds_read_b128 v[204:207], v178 offset:5120
	ds_read_b128 v[208:211], v178 offset:6144
	ds_read_b128 v[212:215], v178 offset:7168
	global_load_lds_dwordx4 v[216:217], off
	v_lshl_add_u64 v[216:217], s[0:1], 0, v[148:149]
	s_add_i32 m0, s37, 0xe000
	s_nop 0
	global_load_lds_dwordx4 v[216:217], off
	s_waitcnt vmcnt(8)
	s_waitcnt lgkmcnt(0)
	s_barrier
	s_setprio 1
	s_waitcnt lgkmcnt(0)
	v_mfma_f32_16x16x32_bf16 v[128:131], v[132:135], v[184:187], v[128:131]
	v_mfma_f32_16x16x32_bf16 v[124:127], v[156:159], v[184:187], v[124:127]
	v_mfma_f32_16x16x32_bf16 v[112:115], v[132:135], v[192:195], v[112:115]
	v_mfma_f32_16x16x32_bf16 v[108:111], v[156:159], v[192:195], v[108:111]
	v_mfma_f32_16x16x32_bf16 v[96:99], v[132:135], v[200:203], v[96:99]
	v_mfma_f32_16x16x32_bf16 v[92:95], v[156:159], v[200:203], v[92:95]
	v_mfma_f32_16x16x32_bf16 v[80:83], v[132:135], v[208:211], v[80:83]
	v_mfma_f32_16x16x32_bf16 v[76:79], v[156:159], v[208:211], v[76:79]
	v_mfma_f32_16x16x32_bf16 v[128:131], v[152:155], v[188:191], v[128:131]
	v_mfma_f32_16x16x32_bf16 v[124:127], v[160:163], v[188:191], v[124:127]
	v_mfma_f32_16x16x32_bf16 v[112:115], v[152:155], v[196:199], v[112:115]
	v_mfma_f32_16x16x32_bf16 v[108:111], v[160:163], v[196:199], v[108:111]
	v_mfma_f32_16x16x32_bf16 v[96:99], v[152:155], v[204:207], v[96:99]
	v_mfma_f32_16x16x32_bf16 v[92:95], v[160:163], v[204:207], v[92:95]
	v_mfma_f32_16x16x32_bf16 v[80:83], v[152:155], v[212:215], v[80:83]
	v_mfma_f32_16x16x32_bf16 v[76:79], v[160:163], v[212:215], v[76:79]
	v_mfma_f32_16x16x32_bf16 v[120:123], v[164:167], v[184:187], v[120:123]
	v_mfma_f32_16x16x32_bf16 v[116:119], v[172:175], v[184:187], v[116:119]
	v_mfma_f32_16x16x32_bf16 v[104:107], v[164:167], v[192:195], v[104:107]
	v_mfma_f32_16x16x32_bf16 v[100:103], v[172:175], v[192:195], v[100:103]
	v_mfma_f32_16x16x32_bf16 v[88:91], v[164:167], v[200:203], v[88:91]
	v_mfma_f32_16x16x32_bf16 v[84:87], v[172:175], v[200:203], v[84:87]
	v_mfma_f32_16x16x32_bf16 v[72:75], v[164:167], v[208:211], v[72:75]
	v_mfma_f32_16x16x32_bf16 v[68:71], v[172:175], v[208:211], v[68:71]
	v_mfma_f32_16x16x32_bf16 v[120:123], v[168:171], v[188:191], v[120:123]
	v_mfma_f32_16x16x32_bf16 v[116:119], v[180:183], v[188:191], v[116:119]
	v_mfma_f32_16x16x32_bf16 v[104:107], v[168:171], v[196:199], v[104:107]
	v_mfma_f32_16x16x32_bf16 v[100:103], v[180:183], v[196:199], v[100:103]
	v_mfma_f32_16x16x32_bf16 v[88:91], v[168:171], v[204:207], v[88:91]
	v_mfma_f32_16x16x32_bf16 v[84:87], v[180:183], v[204:207], v[84:87]
	v_mfma_f32_16x16x32_bf16 v[72:75], v[168:171], v[212:215], v[72:75]
	v_mfma_f32_16x16x32_bf16 v[68:71], v[180:183], v[212:215], v[68:71]
	s_setprio 0
	s_barrier
	s_add_i32 s50, s50, s36
	v_lshl_add_u64 v[216:217], s[6:7], 0, v[138:139]
	s_mov_b32 m0, s50
	ds_read_b128 v[184:187], v178 offset:16384
	ds_read_b128 v[188:191], v178 offset:17408
	ds_read_b128 v[192:195], v178 offset:18432
	ds_read_b128 v[196:199], v178 offset:19456
	ds_read_b128 v[200:203], v178 offset:20480
	ds_read_b128 v[204:207], v178 offset:21504
	ds_read_b128 v[208:211], v178 offset:22528
	ds_read_b128 v[212:215], v178 offset:23552
	global_load_lds_dwordx4 v[216:217], off
	s_add_i32 m0, s50, 0x2000
	s_add_u32 s50, s6, 0x40000
	v_lshl_add_u64 v[218:219], s[6:7], 0, v[0:1]
	s_addc_u32 s51, s7, 0
	s_add_i32 s52, s52, s36
	global_load_lds_dwordx4 v[218:219], off
	v_lshl_add_u64 v[220:221], s[50:51], 0, v[138:139]
	s_mov_b32 m0, s52
	v_lshl_add_u64 v[224:225], s[8:9], 0, v[136:137]
	global_load_lds_dwordx4 v[220:221], off
	v_lshl_add_u64 v[220:221], s[50:51], 0, v[0:1]
	s_add_i32 m0, s52, 0x2000
	s_nop 0
	global_load_lds_dwordx4 v[220:221], off
	v_lshl_add_u64 v[220:221], s[8:9], 0, v[140:141]
	s_waitcnt vmcnt(6)
	s_waitcnt lgkmcnt(0)
	s_barrier
	s_setprio 1
	s_waitcnt lgkmcnt(0)
	v_mfma_f32_16x16x32_bf16 v[64:67], v[132:135], v[184:187], v[64:67]
	v_mfma_f32_16x16x32_bf16 v[60:63], v[156:159], v[184:187], v[60:63]
	v_mfma_f32_16x16x32_bf16 v[48:51], v[132:135], v[192:195], v[48:51]
	v_mfma_f32_16x16x32_bf16 v[44:47], v[156:159], v[192:195], v[44:47]
	v_mfma_f32_16x16x32_bf16 v[32:35], v[132:135], v[200:203], v[32:35]
	v_mfma_f32_16x16x32_bf16 v[28:31], v[156:159], v[200:203], v[28:31]
	v_mfma_f32_16x16x32_bf16 v[16:19], v[132:135], v[208:211], v[16:19]
	v_mfma_f32_16x16x32_bf16 v[12:15], v[156:159], v[208:211], v[12:15]
	v_mfma_f32_16x16x32_bf16 v[64:67], v[152:155], v[188:191], v[64:67]
	v_mfma_f32_16x16x32_bf16 v[60:63], v[160:163], v[188:191], v[60:63]
	v_mfma_f32_16x16x32_bf16 v[48:51], v[152:155], v[196:199], v[48:51]
	v_mfma_f32_16x16x32_bf16 v[44:47], v[160:163], v[196:199], v[44:47]
	v_mfma_f32_16x16x32_bf16 v[32:35], v[152:155], v[204:207], v[32:35]
	v_mfma_f32_16x16x32_bf16 v[28:31], v[160:163], v[204:207], v[28:31]
	v_mfma_f32_16x16x32_bf16 v[16:19], v[152:155], v[212:215], v[16:19]
	v_mfma_f32_16x16x32_bf16 v[12:15], v[160:163], v[212:215], v[12:15]
	v_mfma_f32_16x16x32_bf16 v[56:59], v[164:167], v[184:187], v[56:59]
	v_mfma_f32_16x16x32_bf16 v[52:55], v[172:175], v[184:187], v[52:55]
	v_mfma_f32_16x16x32_bf16 v[40:43], v[164:167], v[192:195], v[40:43]
	v_mfma_f32_16x16x32_bf16 v[36:39], v[172:175], v[192:195], v[36:39]
	v_mfma_f32_16x16x32_bf16 v[24:27], v[164:167], v[200:203], v[24:27]
	v_mfma_f32_16x16x32_bf16 v[20:23], v[172:175], v[200:203], v[20:23]
	v_mfma_f32_16x16x32_bf16 v[8:11], v[164:167], v[208:211], v[8:11]
	v_mfma_f32_16x16x32_bf16 v[4:7], v[172:175], v[208:211], v[4:7]
	v_mfma_f32_16x16x32_bf16 v[56:59], v[168:171], v[188:191], v[56:59]
	v_mfma_f32_16x16x32_bf16 v[52:55], v[180:183], v[188:191], v[52:55]
	v_mfma_f32_16x16x32_bf16 v[40:43], v[168:171], v[196:199], v[40:43]
	v_mfma_f32_16x16x32_bf16 v[36:39], v[180:183], v[196:199], v[36:39]
	v_mfma_f32_16x16x32_bf16 v[24:27], v[168:171], v[204:207], v[24:27]
	v_mfma_f32_16x16x32_bf16 v[20:23], v[180:183], v[204:207], v[20:23]
	v_mfma_f32_16x16x32_bf16 v[8:11], v[168:171], v[212:215], v[8:11]
	v_mfma_f32_16x16x32_bf16 v[4:7], v[180:183], v[212:215], v[4:7]
	s_setprio 0
	s_barrier
.Lb1_ph3:
	s_add_i32 s50, 16, 0x18000
	v_add_u32_e32 v151, s50, v176
	s_add_i32 s51, 16, 0x1c000
	ds_read_b128 v[132:135], v151
	ds_read_b128 v[152:155], v151 offset:1024
	ds_read_b128 v[156:159], v151 offset:2048
	ds_read_b128 v[160:163], v151 offset:3072
	v_add_u32_e32 v151, s51, v176
	ds_read_b128 v[164:167], v151
	ds_read_b128 v[168:171], v151 offset:1024
	ds_read_b128 v[172:175], v151 offset:2048
	ds_read_b128 v[180:183], v151 offset:3072
	s_mov_b32 m0, s37
	s_nop 0
	global_load_lds_dwordx4 v[220:221], off
	s_mov_b32 m0, s38
	s_nop 0
	global_load_lds_dwordx4 v[224:225], off
	s_add_u32 s8, s8, 0x40000
	s_addc_u32 s9, s9, 0
	s_mov_b32 m0, s39
	v_lshl_add_u64 v[226:227], s[8:9], 0, v[140:141]
	ds_read_b128 v[184:187], v178 offset:32768
	ds_read_b128 v[188:191], v178 offset:33792
	ds_read_b128 v[192:195], v178 offset:34816
	ds_read_b128 v[196:199], v178 offset:35840
	ds_read_b128 v[200:203], v178 offset:36864
	ds_read_b128 v[204:207], v178 offset:37888
	ds_read_b128 v[208:211], v178 offset:38912
	ds_read_b128 v[212:215], v178 offset:39936
	global_load_lds_dwordx4 v[226:227], off
	v_lshl_add_u64 v[226:227], s[8:9], 0, v[136:137]
	s_mov_b32 m0, s40
	s_nop 0
	global_load_lds_dwordx4 v[226:227], off
	s_waitcnt vmcnt(8)
	s_waitcnt lgkmcnt(0)
	s_barrier
	s_setprio 1
	s_waitcnt lgkmcnt(0)
	v_mfma_f32_16x16x32_bf16 v[128:131], v[132:135], v[184:187], v[128:131]
	v_mfma_f32_16x16x32_bf16 v[124:127], v[156:159], v[184:187], v[124:127]
	v_mfma_f32_16x16x32_bf16 v[112:115], v[132:135], v[192:195], v[112:115]
	v_mfma_f32_16x16x32_bf16 v[108:111], v[156:159], v[192:195], v[108:111]
	v_mfma_f32_16x16x32_bf16 v[96:99], v[132:135], v[200:203], v[96:99]
	v_mfma_f32_16x16x32_bf16 v[92:95], v[156:159], v[200:203], v[92:95]
	v_mfma_f32_16x16x32_bf16 v[80:83], v[132:135], v[208:211], v[80:83]
	v_mfma_f32_16x16x32_bf16 v[76:79], v[156:159], v[208:211], v[76:79]
	v_mfma_f32_16x16x32_bf16 v[128:131], v[152:155], v[188:191], v[128:131]
	v_mfma_f32_16x16x32_bf16 v[124:127], v[160:163], v[188:191], v[124:127]
	v_mfma_f32_16x16x32_bf16 v[112:115], v[152:155], v[196:199], v[112:115]
	v_mfma_f32_16x16x32_bf16 v[108:111], v[160:163], v[196:199], v[108:111]
	v_mfma_f32_16x16x32_bf16 v[96:99], v[152:155], v[204:207], v[96:99]
	v_mfma_f32_16x16x32_bf16 v[92:95], v[160:163], v[204:207], v[92:95]
	v_mfma_f32_16x16x32_bf16 v[80:83], v[152:155], v[212:215], v[80:83]
	v_mfma_f32_16x16x32_bf16 v[76:79], v[160:163], v[212:215], v[76:79]
	v_mfma_f32_16x16x32_bf16 v[120:123], v[164:167], v[184:187], v[120:123]
	v_mfma_f32_16x16x32_bf16 v[116:119], v[172:175], v[184:187], v[116:119]
	v_mfma_f32_16x16x32_bf16 v[104:107], v[164:167], v[192:195], v[104:107]
	v_mfma_f32_16x16x32_bf16 v[100:103], v[172:175], v[192:195], v[100:103]
	v_mfma_f32_16x16x32_bf16 v[88:91], v[164:167], v[200:203], v[88:91]
	v_mfma_f32_16x16x32_bf16 v[84:87], v[172:175], v[200:203], v[84:87]
	v_mfma_f32_16x16x32_bf16 v[72:75], v[164:167], v[208:211], v[72:75]
	v_mfma_f32_16x16x32_bf16 v[68:71], v[172:175], v[208:211], v[68:71]
	v_mfma_f32_16x16x32_bf16 v[120:123], v[168:171], v[188:191], v[120:123]
	v_mfma_f32_16x16x32_bf16 v[116:119], v[180:183], v[188:191], v[116:119]
	v_mfma_f32_16x16x32_bf16 v[104:107], v[168:171], v[196:199], v[104:107]
	v_mfma_f32_16x16x32_bf16 v[100:103], v[180:183], v[196:199], v[100:103]
	v_mfma_f32_16x16x32_bf16 v[88:91], v[168:171], v[204:207], v[88:91]
	v_mfma_f32_16x16x32_bf16 v[84:87], v[180:183], v[204:207], v[84:87]
	v_mfma_f32_16x16x32_bf16 v[72:75], v[168:171], v[212:215], v[72:75]
	v_mfma_f32_16x16x32_bf16 v[68:71], v[180:183], v[212:215], v[68:71]
	s_setprio 0
	s_barrier
	s_add_i32 s8, s50, s36
	v_lshl_add_u64 v[216:217], v[216:217], 0, s[84:85]
	s_mov_b32 m0, s8
	ds_read_b128 v[184:187], v178 offset:49152
	ds_read_b128 v[188:191], v178 offset:50176
	ds_read_b128 v[192:195], v178 offset:51200
	ds_read_b128 v[196:199], v178 offset:52224
	ds_read_b128 v[200:203], v178 offset:53248
	ds_read_b128 v[204:207], v178 offset:54272
	ds_read_b128 v[208:211], v178 offset:55296
	ds_read_b128 v[212:215], v178 offset:56320
	global_load_lds_dwordx4 v[216:217], off
	s_add_i32 m0, s8, 0x2000
	s_add_u32 s6, s6, 0x40080
	v_lshl_add_u64 v[216:217], v[218:219], 0, s[84:85]
	s_addc_u32 s7, s7, 0
	s_add_i32 s8, s51, s36
	global_load_lds_dwordx4 v[216:217], off
	v_lshl_add_u64 v[216:217], s[6:7], 0, v[138:139]
	s_mov_b32 m0, s8
	s_nop 0
	global_load_lds_dwordx4 v[216:217], off
	v_lshl_add_u64 v[216:217], s[6:7], 0, v[0:1]
	s_add_i32 m0, s8, 0x2000
	s_nop 0
	global_load_lds_dwordx4 v[216:217], off
	v_lshl_add_u64 v[216:217], v[220:221], 0, s[84:85]
	s_mov_b32 m0, s44
	s_nop 0
	global_load_lds_dwordx4 v[216:217], off
	v_lshl_add_u64 v[216:217], v[224:225], 0, s[84:85]
	s_mov_b32 m0, s45
	s_nop 0
	global_load_lds_dwordx4 v[216:217], off
	s_waitcnt vmcnt(8)
	s_waitcnt lgkmcnt(0)
	s_barrier
	s_setprio 1
	s_waitcnt lgkmcnt(0)
	v_mfma_f32_16x16x32_bf16 v[64:67], v[132:135], v[184:187], v[64:67]
	v_mfma_f32_16x16x32_bf16 v[60:63], v[156:159], v[184:187], v[60:63]
	v_mfma_f32_16x16x32_bf16 v[48:51], v[132:135], v[192:195], v[48:51]
	v_mfma_f32_16x16x32_bf16 v[44:47], v[156:159], v[192:195], v[44:47]
	v_mfma_f32_16x16x32_bf16 v[32:35], v[132:135], v[200:203], v[32:35]
	v_mfma_f32_16x16x32_bf16 v[28:31], v[156:159], v[200:203], v[28:31]
	v_mfma_f32_16x16x32_bf16 v[16:19], v[132:135], v[208:211], v[16:19]
	v_mfma_f32_16x16x32_bf16 v[12:15], v[156:159], v[208:211], v[12:15]
	v_mfma_f32_16x16x32_bf16 v[64:67], v[152:155], v[188:191], v[64:67]
	v_mfma_f32_16x16x32_bf16 v[60:63], v[160:163], v[188:191], v[60:63]
	v_mfma_f32_16x16x32_bf16 v[48:51], v[152:155], v[196:199], v[48:51]
	v_mfma_f32_16x16x32_bf16 v[44:47], v[160:163], v[196:199], v[44:47]
	v_mfma_f32_16x16x32_bf16 v[32:35], v[152:155], v[204:207], v[32:35]
	v_mfma_f32_16x16x32_bf16 v[28:31], v[160:163], v[204:207], v[28:31]
	v_mfma_f32_16x16x32_bf16 v[16:19], v[152:155], v[212:215], v[16:19]
	v_mfma_f32_16x16x32_bf16 v[12:15], v[160:163], v[212:215], v[12:15]
	v_mfma_f32_16x16x32_bf16 v[56:59], v[164:167], v[184:187], v[56:59]
	v_mfma_f32_16x16x32_bf16 v[52:55], v[172:175], v[184:187], v[52:55]
	v_mfma_f32_16x16x32_bf16 v[40:43], v[164:167], v[192:195], v[40:43]
	v_mfma_f32_16x16x32_bf16 v[36:39], v[172:175], v[192:195], v[36:39]
	v_mfma_f32_16x16x32_bf16 v[24:27], v[164:167], v[200:203], v[24:27]
	v_mfma_f32_16x16x32_bf16 v[20:23], v[172:175], v[200:203], v[20:23]
	v_mfma_f32_16x16x32_bf16 v[8:11], v[164:167], v[208:211], v[8:11]
	v_mfma_f32_16x16x32_bf16 v[4:7], v[172:175], v[208:211], v[4:7]
	v_mfma_f32_16x16x32_bf16 v[56:59], v[168:171], v[188:191], v[56:59]
	v_mfma_f32_16x16x32_bf16 v[52:55], v[180:183], v[188:191], v[52:55]
	v_mfma_f32_16x16x32_bf16 v[40:43], v[168:171], v[196:199], v[40:43]
	v_mfma_f32_16x16x32_bf16 v[36:39], v[180:183], v[196:199], v[36:39]
	v_mfma_f32_16x16x32_bf16 v[24:27], v[168:171], v[204:207], v[24:27]
	v_mfma_f32_16x16x32_bf16 v[20:23], v[180:183], v[204:207], v[20:23]
	v_mfma_f32_16x16x32_bf16 v[8:11], v[168:171], v[212:215], v[8:11]
	v_mfma_f32_16x16x32_bf16 v[4:7], v[180:183], v[212:215], v[4:7]
	s_setprio 0
	s_barrier
	s_add_i32 s49, s49, 2
	s_add_u32 s0, s0, 0x100
	s_addc_u32 s1, s1, 0
	s_add_u32 s29, s29, 0x100
	s_addc_u32 s42, s42, 0
	s_cmp_gt_u32 s49, 13
	s_cbranch_scc0 .LBB0_156
	s_and_b64 vcc, exec, s[18:19]
	s_cbranch_vccz .LBB0_159
	s_barrier

.LBB0_445:
	s_ashr_i32 s23, s22, 31
	s_lshl_b64 s[24:25], s[22:23], 19
	s_add_u32 s24, s34, s24
	s_addc_u32 s25, s35, s25
	s_and_b64 s[26:27], s[6:7], exec
	s_cselect_b32 s3, s25, s1
	s_cselect_b32 s23, s24, s0
	s_ashr_i32 s21, s20, 31
	s_lshl_b64 s[26:27], s[20:21], 19
	s_add_u32 s26, s36, s26
	s_addc_u32 s27, s37, s27
	s_and_b64 s[30:31], s[6:7], exec
	s_cselect_b32 s21, s27, s29
	s_cselect_b32 s48, s26, s28
	s_add_u32 s0, s0, 0x40080
	s_addc_u32 s1, s1, 0
	s_add_u32 s49, s28, 0x100
	s_addc_u32 s50, s29, 0
	s_mov_b32 s51, -2
	s_waitcnt vmcnt(0)
	s_add_u32 s28, s0, 0xfffc0080
	s_addc_u32 s29, s1, -1
	s_add_i32 s52, 16, 0x10000
	s_cmp_eq_u32 s51, 12
	s_cselect_b32 s31, s3, s29
	s_cselect_b32 s30, s23, s28
	v_add_u32_e32 v3, s52, v175
	s_cselect_b32 s29, s21, s50
	s_cselect_b32 s28, s48, s49
	s_add_i32 s54, 16, 0x14000
	ds_read_b128 v[142:145], v3
	ds_read_b128 v[146:149], v3 offset:1024
	ds_read_b128 v[150:153], v3 offset:2048
	ds_read_b128 v[154:157], v3 offset:3072
	v_add_u32_e32 v3, s54, v175
	ds_read_b128 v[158:161], v3
	ds_read_b128 v[162:165], v3 offset:1024
	ds_read_b128 v[166:169], v3 offset:2048
	ds_read_b128 v[170:173], v3 offset:3072
	v_lshl_add_u64 v[210:211], s[0:1], 0, v[138:139]
	s_add_i32 m0, s39, 0xc000
	ds_read_b128 v[178:181], v177
	ds_read_b128 v[182:185], v177 offset:1024
	ds_read_b128 v[186:189], v177 offset:2048
	ds_read_b128 v[190:193], v177 offset:3072
	ds_read_b128 v[194:197], v177 offset:4096
	ds_read_b128 v[198:201], v177 offset:5120
	ds_read_b128 v[202:205], v177 offset:6144
	ds_read_b128 v[206:209], v177 offset:7168
	global_load_lds_dwordx4 v[210:211], off
	v_lshl_add_u64 v[210:211], s[0:1], 0, v[140:141]
	s_add_i32 m0, s39, 0xe000
	s_nop 0
	global_load_lds_dwordx4 v[210:211], off
	s_waitcnt vmcnt(8)
	s_waitcnt lgkmcnt(0)
	s_barrier
	s_setprio 1
	s_waitcnt lgkmcnt(0)
	v_mfma_f32_16x16x32_bf16 v[128:131], v[142:145], v[178:181], 0
	v_mfma_f32_16x16x32_bf16 v[120:123], v[150:153], v[178:181], 0
	v_mfma_f32_16x16x32_bf16 v[112:115], v[142:145], v[186:189], 0
	v_mfma_f32_16x16x32_bf16 v[104:107], v[150:153], v[186:189], 0
	v_mfma_f32_16x16x32_bf16 v[96:99], v[142:145], v[194:197], 0
	v_mfma_f32_16x16x32_bf16 v[88:91], v[150:153], v[194:197], 0
	v_mfma_f32_16x16x32_bf16 v[80:83], v[142:145], v[202:205], 0
	v_mfma_f32_16x16x32_bf16 v[72:75], v[150:153], v[202:205], 0
	v_mfma_f32_16x16x32_bf16 v[128:131], v[146:149], v[182:185], v[128:131]
	v_mfma_f32_16x16x32_bf16 v[120:123], v[154:157], v[182:185], v[120:123]
	v_mfma_f32_16x16x32_bf16 v[112:115], v[146:149], v[190:193], v[112:115]
	v_mfma_f32_16x16x32_bf16 v[104:107], v[154:157], v[190:193], v[104:107]
	v_mfma_f32_16x16x32_bf16 v[96:99], v[146:149], v[198:201], v[96:99]
	v_mfma_f32_16x16x32_bf16 v[88:91], v[154:157], v[198:201], v[88:91]
	v_mfma_f32_16x16x32_bf16 v[80:83], v[146:149], v[206:209], v[80:83]
	v_mfma_f32_16x16x32_bf16 v[72:75], v[154:157], v[206:209], v[72:75]
	v_mfma_f32_16x16x32_bf16 v[124:127], v[158:161], v[178:181], 0
	v_mfma_f32_16x16x32_bf16 v[116:119], v[166:169], v[178:181], 0
	v_mfma_f32_16x16x32_bf16 v[108:111], v[158:161], v[186:189], 0
	v_mfma_f32_16x16x32_bf16 v[100:103], v[166:169], v[186:189], 0
	v_mfma_f32_16x16x32_bf16 v[92:95], v[158:161], v[194:197], 0
	v_mfma_f32_16x16x32_bf16 v[84:87], v[166:169], v[194:197], 0
	v_mfma_f32_16x16x32_bf16 v[76:79], v[158:161], v[202:205], 0
	v_mfma_f32_16x16x32_bf16 v[68:71], v[166:169], v[202:205], 0
	v_mfma_f32_16x16x32_bf16 v[124:127], v[162:165], v[182:185], v[124:127]
	v_mfma_f32_16x16x32_bf16 v[116:119], v[170:173], v[182:185], v[116:119]
	v_mfma_f32_16x16x32_bf16 v[108:111], v[162:165], v[190:193], v[108:111]
	v_mfma_f32_16x16x32_bf16 v[100:103], v[170:173], v[190:193], v[100:103]
	v_mfma_f32_16x16x32_bf16 v[92:95], v[162:165], v[198:201], v[92:95]
	v_mfma_f32_16x16x32_bf16 v[84:87], v[170:173], v[198:201], v[84:87]
	v_mfma_f32_16x16x32_bf16 v[76:79], v[162:165], v[206:209], v[76:79]
	v_mfma_f32_16x16x32_bf16 v[68:71], v[170:173], v[206:209], v[68:71]
	s_setprio 0
	s_barrier
	s_add_i32 s52, s52, s38
	v_lshl_add_u64 v[210:211], s[28:29], 0, v[134:135]
	s_mov_b32 m0, s52
	ds_read_b128 v[178:181], v177 offset:16384
	ds_read_b128 v[182:185], v177 offset:17408
	ds_read_b128 v[186:189], v177 offset:18432
	ds_read_b128 v[190:193], v177 offset:19456
	ds_read_b128 v[194:197], v177 offset:20480
	ds_read_b128 v[198:201], v177 offset:21504
	ds_read_b128 v[202:205], v177 offset:22528
	ds_read_b128 v[206:209], v177 offset:23552
	global_load_lds_dwordx4 v[210:211], off
	s_add_i32 m0, s52, 0x2000
	s_add_u32 s52, s28, 0x40000
	v_lshl_add_u64 v[212:213], s[28:29], 0, v[0:1]
	s_addc_u32 s53, s29, 0
	s_add_i32 s54, s54, s38
	global_load_lds_dwordx4 v[212:213], off
	v_lshl_add_u64 v[214:215], s[52:53], 0, v[134:135]
	s_mov_b32 m0, s54
	v_lshl_add_u64 v[216:217], s[30:31], 0, v[132:133]
	global_load_lds_dwordx4 v[214:215], off
	v_lshl_add_u64 v[214:215], s[52:53], 0, v[0:1]
	s_add_i32 m0, s54, 0x2000
	s_nop 0
	global_load_lds_dwordx4 v[214:215], off
	v_lshl_add_u64 v[214:215], s[30:31], 0, v[136:137]
	s_waitcnt vmcnt(6)
	s_waitcnt lgkmcnt(0)
	s_barrier
	s_setprio 1
	s_waitcnt lgkmcnt(0)
	v_mfma_f32_16x16x32_bf16 v[64:67], v[142:145], v[178:181], 0
	v_mfma_f32_16x16x32_bf16 v[56:59], v[150:153], v[178:181], 0
	v_mfma_f32_16x16x32_bf16 v[48:51], v[142:145], v[186:189], 0
	v_mfma_f32_16x16x32_bf16 v[40:43], v[150:153], v[186:189], 0
	v_mfma_f32_16x16x32_bf16 v[32:35], v[142:145], v[194:197], 0
	v_mfma_f32_16x16x32_bf16 v[24:27], v[150:153], v[194:197], 0
	v_mfma_f32_16x16x32_bf16 v[16:19], v[142:145], v[202:205], 0
	v_mfma_f32_16x16x32_bf16 v[8:11], v[150:153], v[202:205], 0
	v_mfma_f32_16x16x32_bf16 v[64:67], v[146:149], v[182:185], v[64:67]
	v_mfma_f32_16x16x32_bf16 v[56:59], v[154:157], v[182:185], v[56:59]
	v_mfma_f32_16x16x32_bf16 v[48:51], v[146:149], v[190:193], v[48:51]
	v_mfma_f32_16x16x32_bf16 v[40:43], v[154:157], v[190:193], v[40:43]
	v_mfma_f32_16x16x32_bf16 v[32:35], v[146:149], v[198:201], v[32:35]
	v_mfma_f32_16x16x32_bf16 v[24:27], v[154:157], v[198:201], v[24:27]
	v_mfma_f32_16x16x32_bf16 v[16:19], v[146:149], v[206:209], v[16:19]
	v_mfma_f32_16x16x32_bf16 v[8:11], v[154:157], v[206:209], v[8:11]
	v_mfma_f32_16x16x32_bf16 v[60:63], v[158:161], v[178:181], 0
	v_mfma_f32_16x16x32_bf16 v[52:55], v[166:169], v[178:181], 0
	v_mfma_f32_16x16x32_bf16 v[44:47], v[158:161], v[186:189], 0
	v_mfma_f32_16x16x32_bf16 v[36:39], v[166:169], v[186:189], 0
	v_mfma_f32_16x16x32_bf16 v[28:31], v[158:161], v[194:197], 0
	v_mfma_f32_16x16x32_bf16 v[20:23], v[166:169], v[194:197], 0
	v_mfma_f32_16x16x32_bf16 v[12:15], v[158:161], v[202:205], 0
	v_mfma_f32_16x16x32_bf16 v[4:7], v[166:169], v[202:205], 0
	v_mfma_f32_16x16x32_bf16 v[60:63], v[162:165], v[182:185], v[60:63]
	v_mfma_f32_16x16x32_bf16 v[52:55], v[170:173], v[182:185], v[52:55]
	v_mfma_f32_16x16x32_bf16 v[44:47], v[162:165], v[190:193], v[44:47]
	v_mfma_f32_16x16x32_bf16 v[36:39], v[170:173], v[190:193], v[36:39]
	v_mfma_f32_16x16x32_bf16 v[28:31], v[162:165], v[198:201], v[28:31]
	v_mfma_f32_16x16x32_bf16 v[20:23], v[170:173], v[198:201], v[20:23]
	v_mfma_f32_16x16x32_bf16 v[12:15], v[162:165], v[206:209], v[12:15]
	v_mfma_f32_16x16x32_bf16 v[4:7], v[170:173], v[206:209], v[4:7]
	s_setprio 0
	s_barrier
	s_branch .La1_ph3
.LBB0_446:
	s_add_u32 s28, s0, 0xfffc0080
	s_addc_u32 s29, s1, -1
	s_add_i32 s52, 16, 0x10000
	s_cmp_eq_u32 s51, 12
	s_cselect_b32 s31, s3, s29
	s_cselect_b32 s30, s23, s28
	v_add_u32_e32 v3, s52, v175
	s_cselect_b32 s29, s21, s50
	s_cselect_b32 s28, s48, s49
	s_add_i32 s54, 16, 0x14000
	ds_read_b128 v[142:145], v3
	ds_read_b128 v[146:149], v3 offset:1024
	ds_read_b128 v[150:153], v3 offset:2048
	ds_read_b128 v[154:157], v3 offset:3072
	v_add_u32_e32 v3, s54, v175
	ds_read_b128 v[158:161], v3
	ds_read_b128 v[162:165], v3 offset:1024
	ds_read_b128 v[166:169], v3 offset:2048
	ds_read_b128 v[170:173], v3 offset:3072
	v_lshl_add_u64 v[210:211], s[0:1], 0, v[138:139]
	s_add_i32 m0, s39, 0xc000
	ds_read_b128 v[178:181], v177
	ds_read_b128 v[182:185], v177 offset:1024
	ds_read_b128 v[186:189], v177 offset:2048
	ds_read_b128 v[190:193], v177 offset:3072
	ds_read_b128 v[194:197], v177 offset:4096
	ds_read_b128 v[198:201], v177 offset:5120
	ds_read_b128 v[202:205], v177 offset:6144
	ds_read_b128 v[206:209], v177 offset:7168
	global_load_lds_dwordx4 v[210:211], off
	v_lshl_add_u64 v[210:211], s[0:1], 0, v[140:141]
	s_add_i32 m0, s39, 0xe000
	s_nop 0
	global_load_lds_dwordx4 v[210:211], off
	s_waitcnt vmcnt(8)
	s_waitcnt lgkmcnt(0)
	s_barrier
	s_setprio 1
	s_waitcnt lgkmcnt(0)
	v_mfma_f32_16x16x32_bf16 v[128:131], v[142:145], v[178:181], v[128:131]
	v_mfma_f32_16x16x32_bf16 v[120:123], v[150:153], v[178:181], v[120:123]
	v_mfma_f32_16x16x32_bf16 v[112:115], v[142:145], v[186:189], v[112:115]
	v_mfma_f32_16x16x32_bf16 v[104:107], v[150:153], v[186:189], v[104:107]
	v_mfma_f32_16x16x32_bf16 v[96:99], v[142:145], v[194:197], v[96:99]
	v_mfma_f32_16x16x32_bf16 v[88:91], v[150:153], v[194:197], v[88:91]
	v_mfma_f32_16x16x32_bf16 v[80:83], v[142:145], v[202:205], v[80:83]
	v_mfma_f32_16x16x32_bf16 v[72:75], v[150:153], v[202:205], v[72:75]
	v_mfma_f32_16x16x32_bf16 v[128:131], v[146:149], v[182:185], v[128:131]
	v_mfma_f32_16x16x32_bf16 v[120:123], v[154:157], v[182:185], v[120:123]
	v_mfma_f32_16x16x32_bf16 v[112:115], v[146:149], v[190:193], v[112:115]
	v_mfma_f32_16x16x32_bf16 v[104:107], v[154:157], v[190:193], v[104:107]
	v_mfma_f32_16x16x32_bf16 v[96:99], v[146:149], v[198:201], v[96:99]
	v_mfma_f32_16x16x32_bf16 v[88:91], v[154:157], v[198:201], v[88:91]
	v_mfma_f32_16x16x32_bf16 v[80:83], v[146:149], v[206:209], v[80:83]
	v_mfma_f32_16x16x32_bf16 v[72:75], v[154:157], v[206:209], v[72:75]
	v_mfma_f32_16x16x32_bf16 v[124:127], v[158:161], v[178:181], v[124:127]
	v_mfma_f32_16x16x32_bf16 v[116:119], v[166:169], v[178:181], v[116:119]
	v_mfma_f32_16x16x32_bf16 v[108:111], v[158:161], v[186:189], v[108:111]
	v_mfma_f32_16x16x32_bf16 v[100:103], v[166:169], v[186:189], v[100:103]
	v_mfma_f32_16x16x32_bf16 v[92:95], v[158:161], v[194:197], v[92:95]
	v_mfma_f32_16x16x32_bf16 v[84:87], v[166:169], v[194:197], v[84:87]
	v_mfma_f32_16x16x32_bf16 v[76:79], v[158:161], v[202:205], v[76:79]
	v_mfma_f32_16x16x32_bf16 v[68:71], v[166:169], v[202:205], v[68:71]
	v_mfma_f32_16x16x32_bf16 v[124:127], v[162:165], v[182:185], v[124:127]
	v_mfma_f32_16x16x32_bf16 v[116:119], v[170:173], v[182:185], v[116:119]
	v_mfma_f32_16x16x32_bf16 v[108:111], v[162:165], v[190:193], v[108:111]
	v_mfma_f32_16x16x32_bf16 v[100:103], v[170:173], v[190:193], v[100:103]
	v_mfma_f32_16x16x32_bf16 v[92:95], v[162:165], v[198:201], v[92:95]
	v_mfma_f32_16x16x32_bf16 v[84:87], v[170:173], v[198:201], v[84:87]
	v_mfma_f32_16x16x32_bf16 v[76:79], v[162:165], v[206:209], v[76:79]
	v_mfma_f32_16x16x32_bf16 v[68:71], v[170:173], v[206:209], v[68:71]
	s_setprio 0
	s_barrier
	s_add_i32 s52, s52, s38
	v_lshl_add_u64 v[210:211], s[28:29], 0, v[134:135]
	s_mov_b32 m0, s52
	ds_read_b128 v[178:181], v177 offset:16384
	ds_read_b128 v[182:185], v177 offset:17408
	ds_read_b128 v[186:189], v177 offset:18432
	ds_read_b128 v[190:193], v177 offset:19456
	ds_read_b128 v[194:197], v177 offset:20480
	ds_read_b128 v[198:201], v177 offset:21504
	ds_read_b128 v[202:205], v177 offset:22528
	ds_read_b128 v[206:209], v177 offset:23552
	global_load_lds_dwordx4 v[210:211], off
	s_add_i32 m0, s52, 0x2000
	s_add_u32 s52, s28, 0x40000
	v_lshl_add_u64 v[212:213], s[28:29], 0, v[0:1]
	s_addc_u32 s53, s29, 0
	s_add_i32 s54, s54, s38
	global_load_lds_dwordx4 v[212:213], off
	v_lshl_add_u64 v[214:215], s[52:53], 0, v[134:135]
	s_mov_b32 m0, s54
	v_lshl_add_u64 v[216:217], s[30:31], 0, v[132:133]
	global_load_lds_dwordx4 v[214:215], off
	v_lshl_add_u64 v[214:215], s[52:53], 0, v[0:1]
	s_add_i32 m0, s54, 0x2000
	s_nop 0
	global_load_lds_dwordx4 v[214:215], off
	v_lshl_add_u64 v[214:215], s[30:31], 0, v[136:137]
	s_waitcnt vmcnt(6)
	s_waitcnt lgkmcnt(0)
	s_barrier
	s_setprio 1
	s_waitcnt lgkmcnt(0)
	v_mfma_f32_16x16x32_bf16 v[64:67], v[142:145], v[178:181], v[64:67]
	v_mfma_f32_16x16x32_bf16 v[56:59], v[150:153], v[178:181], v[56:59]
	v_mfma_f32_16x16x32_bf16 v[48:51], v[142:145], v[186:189], v[48:51]
	v_mfma_f32_16x16x32_bf16 v[40:43], v[150:153], v[186:189], v[40:43]
	v_mfma_f32_16x16x32_bf16 v[32:35], v[142:145], v[194:197], v[32:35]
	v_mfma_f32_16x16x32_bf16 v[24:27], v[150:153], v[194:197], v[24:27]
	v_mfma_f32_16x16x32_bf16 v[16:19], v[142:145], v[202:205], v[16:19]
	v_mfma_f32_16x16x32_bf16 v[8:11], v[150:153], v[202:205], v[8:11]
	v_mfma_f32_16x16x32_bf16 v[64:67], v[146:149], v[182:185], v[64:67]
	v_mfma_f32_16x16x32_bf16 v[56:59], v[154:157], v[182:185], v[56:59]
	v_mfma_f32_16x16x32_bf16 v[48:51], v[146:149], v[190:193], v[48:51]
	v_mfma_f32_16x16x32_bf16 v[40:43], v[154:157], v[190:193], v[40:43]
	v_mfma_f32_16x16x32_bf16 v[32:35], v[146:149], v[198:201], v[32:35]
	v_mfma_f32_16x16x32_bf16 v[24:27], v[154:157], v[198:201], v[24:27]
	v_mfma_f32_16x16x32_bf16 v[16:19], v[146:149], v[206:209], v[16:19]
	v_mfma_f32_16x16x32_bf16 v[8:11], v[154:157], v[206:209], v[8:11]
	v_mfma_f32_16x16x32_bf16 v[60:63], v[158:161], v[178:181], v[60:63]
	v_mfma_f32_16x16x32_bf16 v[52:55], v[166:169], v[178:181], v[52:55]
	v_mfma_f32_16x16x32_bf16 v[44:47], v[158:161], v[186:189], v[44:47]
	v_mfma_f32_16x16x32_bf16 v[36:39], v[166:169], v[186:189], v[36:39]
	v_mfma_f32_16x16x32_bf16 v[28:31], v[158:161], v[194:197], v[28:31]
	v_mfma_f32_16x16x32_bf16 v[20:23], v[166:169], v[194:197], v[20:23]
	v_mfma_f32_16x16x32_bf16 v[12:15], v[158:161], v[202:205], v[12:15]
	v_mfma_f32_16x16x32_bf16 v[4:7], v[166:169], v[202:205], v[4:7]
	v_mfma_f32_16x16x32_bf16 v[60:63], v[162:165], v[182:185], v[60:63]
	v_mfma_f32_16x16x32_bf16 v[52:55], v[170:173], v[182:185], v[52:55]
	v_mfma_f32_16x16x32_bf16 v[44:47], v[162:165], v[190:193], v[44:47]
	v_mfma_f32_16x16x32_bf16 v[36:39], v[170:173], v[190:193], v[36:39]
	v_mfma_f32_16x16x32_bf16 v[28:31], v[162:165], v[198:201], v[28:31]
	v_mfma_f32_16x16x32_bf16 v[20:23], v[170:173], v[198:201], v[20:23]
	v_mfma_f32_16x16x32_bf16 v[12:15], v[162:165], v[206:209], v[12:15]
	v_mfma_f32_16x16x32_bf16 v[4:7], v[170:173], v[206:209], v[4:7]
	s_setprio 0
	s_barrier
.La1_ph3:
	s_add_i32 s52, 16, 0x18000
	v_add_u32_e32 v3, s52, v175
	s_add_i32 s53, 16, 0x1c000
	ds_read_b128 v[142:145], v3
	ds_read_b128 v[146:149], v3 offset:1024
	ds_read_b128 v[150:153], v3 offset:2048
	ds_read_b128 v[154:157], v3 offset:3072
	v_add_u32_e32 v3, s53, v175
	ds_read_b128 v[158:161], v3
	ds_read_b128 v[162:165], v3 offset:1024
	ds_read_b128 v[166:169], v3 offset:2048
	ds_read_b128 v[170:173], v3 offset:3072
	s_mov_b32 m0, s39
	s_nop 0
	global_load_lds_dwordx4 v[214:215], off
	s_mov_b32 m0, s40
	s_nop 0
	global_load_lds_dwordx4 v[216:217], off
	s_add_u32 s30, s30, 0x40000
	s_addc_u32 s31, s31, 0
	s_mov_b32 m0, s41
	v_lshl_add_u64 v[218:219], s[30:31], 0, v[136:137]
	ds_read_b128 v[178:181], v177 offset:32768
	ds_read_b128 v[182:185], v177 offset:33792
	ds_read_b128 v[186:189], v177 offset:34816
	ds_read_b128 v[190:193], v177 offset:35840
	ds_read_b128 v[194:197], v177 offset:36864
	ds_read_b128 v[198:201], v177 offset:37888
	ds_read_b128 v[202:205], v177 offset:38912
	ds_read_b128 v[206:209], v177 offset:39936
	global_load_lds_dwordx4 v[218:219], off
	v_lshl_add_u64 v[218:219], s[30:31], 0, v[132:133]
	s_mov_b32 m0, s42
	s_nop 0
	global_load_lds_dwordx4 v[218:219], off
	s_waitcnt vmcnt(8)
	s_waitcnt lgkmcnt(0)
	s_barrier
	s_setprio 1
	s_waitcnt lgkmcnt(0)
	v_mfma_f32_16x16x32_bf16 v[128:131], v[142:145], v[178:181], v[128:131]
	v_mfma_f32_16x16x32_bf16 v[120:123], v[150:153], v[178:181], v[120:123]
	v_mfma_f32_16x16x32_bf16 v[112:115], v[142:145], v[186:189], v[112:115]
	v_mfma_f32_16x16x32_bf16 v[104:107], v[150:153], v[186:189], v[104:107]
	v_mfma_f32_16x16x32_bf16 v[96:99], v[142:145], v[194:197], v[96:99]
	v_mfma_f32_16x16x32_bf16 v[88:91], v[150:153], v[194:197], v[88:91]
	v_mfma_f32_16x16x32_bf16 v[80:83], v[142:145], v[202:205], v[80:83]
	v_mfma_f32_16x16x32_bf16 v[72:75], v[150:153], v[202:205], v[72:75]
	v_mfma_f32_16x16x32_bf16 v[128:131], v[146:149], v[182:185], v[128:131]
	v_mfma_f32_16x16x32_bf16 v[120:123], v[154:157], v[182:185], v[120:123]
	v_mfma_f32_16x16x32_bf16 v[112:115], v[146:149], v[190:193], v[112:115]
	v_mfma_f32_16x16x32_bf16 v[104:107], v[154:157], v[190:193], v[104:107]
	v_mfma_f32_16x16x32_bf16 v[96:99], v[146:149], v[198:201], v[96:99]
	v_mfma_f32_16x16x32_bf16 v[88:91], v[154:157], v[198:201], v[88:91]
	v_mfma_f32_16x16x32_bf16 v[80:83], v[146:149], v[206:209], v[80:83]
	v_mfma_f32_16x16x32_bf16 v[72:75], v[154:157], v[206:209], v[72:75]
	v_mfma_f32_16x16x32_bf16 v[124:127], v[158:161], v[178:181], v[124:127]
	v_mfma_f32_16x16x32_bf16 v[116:119], v[166:169], v[178:181], v[116:119]
	v_mfma_f32_16x16x32_bf16 v[108:111], v[158:161], v[186:189], v[108:111]
	v_mfma_f32_16x16x32_bf16 v[100:103], v[166:169], v[186:189], v[100:103]
	v_mfma_f32_16x16x32_bf16 v[92:95], v[158:161], v[194:197], v[92:95]
	v_mfma_f32_16x16x32_bf16 v[84:87], v[166:169], v[194:197], v[84:87]
	v_mfma_f32_16x16x32_bf16 v[76:79], v[158:161], v[202:205], v[76:79]
	v_mfma_f32_16x16x32_bf16 v[68:71], v[166:169], v[202:205], v[68:71]
	v_mfma_f32_16x16x32_bf16 v[124:127], v[162:165], v[182:185], v[124:127]
	v_mfma_f32_16x16x32_bf16 v[116:119], v[170:173], v[182:185], v[116:119]
	v_mfma_f32_16x16x32_bf16 v[108:111], v[162:165], v[190:193], v[108:111]
	v_mfma_f32_16x16x32_bf16 v[100:103], v[170:173], v[190:193], v[100:103]
	v_mfma_f32_16x16x32_bf16 v[92:95], v[162:165], v[198:201], v[92:95]
	v_mfma_f32_16x16x32_bf16 v[84:87], v[170:173], v[198:201], v[84:87]
	v_mfma_f32_16x16x32_bf16 v[76:79], v[162:165], v[206:209], v[76:79]
	v_mfma_f32_16x16x32_bf16 v[68:71], v[170:173], v[206:209], v[68:71]
	s_setprio 0
	s_barrier
	s_add_i32 s30, s52, s38
	v_lshl_add_u64 v[210:211], v[210:211], 0, s[84:85]
	s_mov_b32 m0, s30
	ds_read_b128 v[178:181], v177 offset:49152
	ds_read_b128 v[182:185], v177 offset:50176
	ds_read_b128 v[186:189], v177 offset:51200
	ds_read_b128 v[190:193], v177 offset:52224
	ds_read_b128 v[194:197], v177 offset:53248
	ds_read_b128 v[198:201], v177 offset:54272
	ds_read_b128 v[202:205], v177 offset:55296
	ds_read_b128 v[206:209], v177 offset:56320
	global_load_lds_dwordx4 v[210:211], off
	s_add_i32 m0, s30, 0x2000
	s_add_u32 s28, s28, 0x40080
	v_lshl_add_u64 v[210:211], v[212:213], 0, s[84:85]
	s_addc_u32 s29, s29, 0
	s_add_i32 s30, s53, s38
	global_load_lds_dwordx4 v[210:211], off
	v_lshl_add_u64 v[210:211], s[28:29], 0, v[134:135]
	s_mov_b32 m0, s30
	s_nop 0
	global_load_lds_dwordx4 v[210:211], off
	v_lshl_add_u64 v[210:211], s[28:29], 0, v[0:1]
	s_add_i32 m0, s30, 0x2000
	s_nop 0
	global_load_lds_dwordx4 v[210:211], off
	v_lshl_add_u64 v[210:211], v[214:215], 0, s[84:85]
	s_mov_b32 m0, s44
	s_nop 0
	global_load_lds_dwordx4 v[210:211], off
	v_lshl_add_u64 v[210:211], v[216:217], 0, s[84:85]
	s_mov_b32 m0, s45
	s_nop 0
	global_load_lds_dwordx4 v[210:211], off
	s_waitcnt vmcnt(8)
	s_waitcnt lgkmcnt(0)
	s_barrier
	s_setprio 1
	s_waitcnt lgkmcnt(0)
	v_mfma_f32_16x16x32_bf16 v[64:67], v[142:145], v[178:181], v[64:67]
	v_mfma_f32_16x16x32_bf16 v[56:59], v[150:153], v[178:181], v[56:59]
	v_mfma_f32_16x16x32_bf16 v[48:51], v[142:145], v[186:189], v[48:51]
	v_mfma_f32_16x16x32_bf16 v[40:43], v[150:153], v[186:189], v[40:43]
	v_mfma_f32_16x16x32_bf16 v[32:35], v[142:145], v[194:197], v[32:35]
	v_mfma_f32_16x16x32_bf16 v[24:27], v[150:153], v[194:197], v[24:27]
	v_mfma_f32_16x16x32_bf16 v[16:19], v[142:145], v[202:205], v[16:19]
	v_mfma_f32_16x16x32_bf16 v[8:11], v[150:153], v[202:205], v[8:11]
	v_mfma_f32_16x16x32_bf16 v[64:67], v[146:149], v[182:185], v[64:67]
	v_mfma_f32_16x16x32_bf16 v[56:59], v[154:157], v[182:185], v[56:59]
	v_mfma_f32_16x16x32_bf16 v[48:51], v[146:149], v[190:193], v[48:51]
	v_mfma_f32_16x16x32_bf16 v[40:43], v[154:157], v[190:193], v[40:43]
	v_mfma_f32_16x16x32_bf16 v[32:35], v[146:149], v[198:201], v[32:35]
	v_mfma_f32_16x16x32_bf16 v[24:27], v[154:157], v[198:201], v[24:27]
	v_mfma_f32_16x16x32_bf16 v[16:19], v[146:149], v[206:209], v[16:19]
	v_mfma_f32_16x16x32_bf16 v[8:11], v[154:157], v[206:209], v[8:11]
	v_mfma_f32_16x16x32_bf16 v[60:63], v[158:161], v[178:181], v[60:63]
	v_mfma_f32_16x16x32_bf16 v[52:55], v[166:169], v[178:181], v[52:55]
	v_mfma_f32_16x16x32_bf16 v[44:47], v[158:161], v[186:189], v[44:47]
	v_mfma_f32_16x16x32_bf16 v[36:39], v[166:169], v[186:189], v[36:39]
	v_mfma_f32_16x16x32_bf16 v[28:31], v[158:161], v[194:197], v[28:31]
	v_mfma_f32_16x16x32_bf16 v[20:23], v[166:169], v[194:197], v[20:23]
	v_mfma_f32_16x16x32_bf16 v[12:15], v[158:161], v[202:205], v[12:15]
	v_mfma_f32_16x16x32_bf16 v[4:7], v[166:169], v[202:205], v[4:7]
	v_mfma_f32_16x16x32_bf16 v[60:63], v[162:165], v[182:185], v[60:63]
	v_mfma_f32_16x16x32_bf16 v[52:55], v[170:173], v[182:185], v[52:55]
	v_mfma_f32_16x16x32_bf16 v[44:47], v[162:165], v[190:193], v[44:47]
	v_mfma_f32_16x16x32_bf16 v[36:39], v[170:173], v[190:193], v[36:39]
	v_mfma_f32_16x16x32_bf16 v[28:31], v[162:165], v[198:201], v[28:31]
	v_mfma_f32_16x16x32_bf16 v[20:23], v[170:173], v[198:201], v[20:23]
	v_mfma_f32_16x16x32_bf16 v[12:15], v[162:165], v[206:209], v[12:15]
	v_mfma_f32_16x16x32_bf16 v[4:7], v[170:173], v[206:209], v[4:7]
	s_setprio 0
	s_barrier
	s_add_i32 s51, s51, 2
	s_add_u32 s0, s0, 0x100
	s_addc_u32 s1, s1, 0
	s_add_u32 s49, s49, 0x100
	s_addc_u32 s50, s50, 0
	s_cmp_gt_u32 s51, 13
	s_cbranch_scc0 .LBB0_446
	s_and_b64 vcc, exec, s[18:19]
	s_cbranch_vccz .LBB0_449
	s_barrier

.LBB0_620:
	s_add_i32 s58, s34, 2
	s_add_u32 s59, s22, s30
	s_addc_u32 s35, s23, s31
	s_add_u32 s60, s0, s30
	s_addc_u32 s61, s1, s31
	s_add_i32 s62, 16, 0x10000
	s_cmp_eq_u32 s54, s34
	s_cselect_b32 s35, s9, s35
	s_cselect_b32 s34, s8, s59
	v_add_u32_e32 v149, s62, v147
	s_cselect_b32 s61, s29, s61
	s_cselect_b32 s60, s28, s60
	s_add_i32 s59, 16, 0x14000
	ds_read_b128 v[150:153], v149
	ds_read_b128 v[154:157], v149 offset:1024
	ds_read_b128 v[158:161], v149 offset:2048
	ds_read_b128 v[162:165], v149 offset:3072
	v_add_u32_e32 v149, s59, v147
	ds_read_b128 v[166:169], v149
	ds_read_b128 v[170:173], v149 offset:1024
	ds_read_b128 v[174:177], v149 offset:2048
	ds_read_b128 v[178:181], v149 offset:3072
	v_lshl_add_u64 v[214:215], s[22:23], 0, v[144:145]
	s_add_i32 m0, s47, 0xc000
	ds_read_b128 v[182:185], v148
	ds_read_b128 v[186:189], v148 offset:1024
	ds_read_b128 v[190:193], v148 offset:2048
	ds_read_b128 v[194:197], v148 offset:3072
	ds_read_b128 v[198:201], v148 offset:4096
	ds_read_b128 v[202:205], v148 offset:5120
	ds_read_b128 v[206:209], v148 offset:6144
	ds_read_b128 v[210:213], v148 offset:7168
	global_load_lds_dwordx4 v[214:215], off
	v_lshl_add_u64 v[214:215], s[22:23], 0, v[142:143]
	s_add_i32 m0, s47, 0xe000
	s_nop 0
	global_load_lds_dwordx4 v[214:215], off
	s_waitcnt vmcnt(8)
	s_waitcnt lgkmcnt(0)
	s_barrier
	s_setprio 1
	s_waitcnt lgkmcnt(0)
	v_mfma_f32_16x16x32_bf16 v[128:131], v[150:153], v[182:185], v[128:131]
	v_mfma_f32_16x16x32_bf16 v[124:127], v[158:161], v[182:185], v[124:127]
	v_mfma_f32_16x16x32_bf16 v[120:123], v[150:153], v[190:193], v[120:123]
	v_mfma_f32_16x16x32_bf16 v[116:119], v[158:161], v[190:193], v[116:119]
	v_mfma_f32_16x16x32_bf16 v[112:115], v[150:153], v[198:201], v[112:115]
	v_mfma_f32_16x16x32_bf16 v[108:111], v[158:161], v[198:201], v[108:111]
	v_mfma_f32_16x16x32_bf16 v[104:107], v[150:153], v[206:209], v[104:107]
	v_mfma_f32_16x16x32_bf16 v[100:103], v[158:161], v[206:209], v[100:103]
	v_mfma_f32_16x16x32_bf16 v[128:131], v[154:157], v[186:189], v[128:131]
	v_mfma_f32_16x16x32_bf16 v[124:127], v[162:165], v[186:189], v[124:127]
	v_mfma_f32_16x16x32_bf16 v[120:123], v[154:157], v[194:197], v[120:123]
	v_mfma_f32_16x16x32_bf16 v[116:119], v[162:165], v[194:197], v[116:119]
	v_mfma_f32_16x16x32_bf16 v[112:115], v[154:157], v[202:205], v[112:115]
	v_mfma_f32_16x16x32_bf16 v[108:111], v[162:165], v[202:205], v[108:111]
	v_mfma_f32_16x16x32_bf16 v[104:107], v[154:157], v[210:213], v[104:107]
	v_mfma_f32_16x16x32_bf16 v[100:103], v[162:165], v[210:213], v[100:103]
	v_mfma_f32_16x16x32_bf16 v[64:67], v[166:169], v[182:185], v[64:67]
	v_mfma_f32_16x16x32_bf16 v[60:63], v[174:177], v[182:185], v[60:63]
	v_mfma_f32_16x16x32_bf16 v[56:59], v[166:169], v[190:193], v[56:59]
	v_mfma_f32_16x16x32_bf16 v[52:55], v[174:177], v[190:193], v[52:55]
	v_mfma_f32_16x16x32_bf16 v[48:51], v[166:169], v[198:201], v[48:51]
	v_mfma_f32_16x16x32_bf16 v[44:47], v[174:177], v[198:201], v[44:47]
	v_mfma_f32_16x16x32_bf16 v[40:43], v[166:169], v[206:209], v[40:43]
	v_mfma_f32_16x16x32_bf16 v[36:39], v[174:177], v[206:209], v[36:39]
	v_mfma_f32_16x16x32_bf16 v[64:67], v[170:173], v[186:189], v[64:67]
	v_mfma_f32_16x16x32_bf16 v[60:63], v[178:181], v[186:189], v[60:63]
	v_mfma_f32_16x16x32_bf16 v[56:59], v[170:173], v[194:197], v[56:59]
	v_mfma_f32_16x16x32_bf16 v[52:55], v[178:181], v[194:197], v[52:55]
	v_mfma_f32_16x16x32_bf16 v[48:51], v[170:173], v[202:205], v[48:51]
	v_mfma_f32_16x16x32_bf16 v[44:47], v[178:181], v[202:205], v[44:47]
	v_mfma_f32_16x16x32_bf16 v[40:43], v[170:173], v[210:213], v[40:43]
	v_mfma_f32_16x16x32_bf16 v[36:39], v[178:181], v[210:213], v[36:39]
	s_setprio 0
	s_barrier
	s_add_i32 s62, s62, s42
	v_lshl_add_u64 v[214:215], s[60:61], 0, v[134:135]
	s_mov_b32 m0, s62
	ds_read_b128 v[182:185], v148 offset:16384
	ds_read_b128 v[186:189], v148 offset:17408
	ds_read_b128 v[190:193], v148 offset:18432
	ds_read_b128 v[194:197], v148 offset:19456
	ds_read_b128 v[198:201], v148 offset:20480
	ds_read_b128 v[202:205], v148 offset:21504
	ds_read_b128 v[206:209], v148 offset:22528
	ds_read_b128 v[210:213], v148 offset:23552
	global_load_lds_dwordx4 v[214:215], off
	s_add_i32 m0, s62, 0x2000
	v_lshl_add_u64 v[216:217], s[60:61], 0, v[0:1]
	s_add_u32 s60, s60, s40
	s_addc_u32 s61, s61, 0
	s_add_i32 s59, s59, s42
	global_load_lds_dwordx4 v[216:217], off
	v_lshl_add_u64 v[218:219], s[60:61], 0, v[134:135]
	s_mov_b32 m0, s59
	v_lshl_add_u64 v[220:221], s[60:61], 0, v[0:1]
	global_load_lds_dwordx4 v[218:219], off
	s_add_i32 m0, s59, 0x2000
	v_lshl_add_u64 v[224:225], s[34:35], 0, v[136:137]
	global_load_lds_dwordx4 v[220:221], off
	v_lshl_add_u64 v[226:227], s[34:35], 0, v[132:133]
	s_waitcnt vmcnt(6)
	s_waitcnt lgkmcnt(0)
	s_barrier
	s_setprio 1
	s_waitcnt lgkmcnt(0)
	v_mfma_f32_16x16x32_bf16 v[96:99], v[150:153], v[182:185], v[96:99]
	v_mfma_f32_16x16x32_bf16 v[92:95], v[158:161], v[182:185], v[92:95]
	v_mfma_f32_16x16x32_bf16 v[88:91], v[150:153], v[190:193], v[88:91]
	v_mfma_f32_16x16x32_bf16 v[84:87], v[158:161], v[190:193], v[84:87]
	v_mfma_f32_16x16x32_bf16 v[80:83], v[150:153], v[198:201], v[80:83]
	v_mfma_f32_16x16x32_bf16 v[76:79], v[158:161], v[198:201], v[76:79]
	v_mfma_f32_16x16x32_bf16 v[72:75], v[150:153], v[206:209], v[72:75]
	v_mfma_f32_16x16x32_bf16 v[68:71], v[158:161], v[206:209], v[68:71]
	v_mfma_f32_16x16x32_bf16 v[96:99], v[154:157], v[186:189], v[96:99]
	v_mfma_f32_16x16x32_bf16 v[92:95], v[162:165], v[186:189], v[92:95]
	v_mfma_f32_16x16x32_bf16 v[88:91], v[154:157], v[194:197], v[88:91]
	v_mfma_f32_16x16x32_bf16 v[84:87], v[162:165], v[194:197], v[84:87]
	v_mfma_f32_16x16x32_bf16 v[80:83], v[154:157], v[202:205], v[80:83]
	v_mfma_f32_16x16x32_bf16 v[76:79], v[162:165], v[202:205], v[76:79]
	v_mfma_f32_16x16x32_bf16 v[72:75], v[154:157], v[210:213], v[72:75]
	v_mfma_f32_16x16x32_bf16 v[68:71], v[162:165], v[210:213], v[68:71]
	v_mfma_f32_16x16x32_bf16 v[32:35], v[166:169], v[182:185], v[32:35]
	v_mfma_f32_16x16x32_bf16 v[28:31], v[174:177], v[182:185], v[28:31]
	v_mfma_f32_16x16x32_bf16 v[24:27], v[166:169], v[190:193], v[24:27]
	v_mfma_f32_16x16x32_bf16 v[20:23], v[174:177], v[190:193], v[20:23]
	v_mfma_f32_16x16x32_bf16 v[16:19], v[166:169], v[198:201], v[16:19]
	v_mfma_f32_16x16x32_bf16 v[12:15], v[174:177], v[198:201], v[12:15]
	v_mfma_f32_16x16x32_bf16 v[8:11], v[166:169], v[206:209], v[8:11]
	v_mfma_f32_16x16x32_bf16 v[4:7], v[174:177], v[206:209], v[4:7]
	v_mfma_f32_16x16x32_bf16 v[32:35], v[170:173], v[186:189], v[32:35]
	v_mfma_f32_16x16x32_bf16 v[28:31], v[178:181], v[186:189], v[28:31]
	v_mfma_f32_16x16x32_bf16 v[24:27], v[170:173], v[194:197], v[24:27]
	v_mfma_f32_16x16x32_bf16 v[20:23], v[178:181], v[194:197], v[20:23]
	v_mfma_f32_16x16x32_bf16 v[16:19], v[170:173], v[202:205], v[16:19]
	v_mfma_f32_16x16x32_bf16 v[12:15], v[178:181], v[202:205], v[12:15]
	v_mfma_f32_16x16x32_bf16 v[8:11], v[170:173], v[210:213], v[8:11]
	v_mfma_f32_16x16x32_bf16 v[4:7], v[178:181], v[210:213], v[4:7]
	s_setprio 0
	s_barrier
	s_add_i32 s59, 16, 0x18000
	v_add_u32_e32 v149, s59, v147
	s_add_i32 s60, 16, 0x1c000
	ds_read_b128 v[150:153], v149
	ds_read_b128 v[154:157], v149 offset:1024
	ds_read_b128 v[158:161], v149 offset:2048
	ds_read_b128 v[162:165], v149 offset:3072
	v_add_u32_e32 v149, s60, v147
	ds_read_b128 v[166:169], v149
	ds_read_b128 v[170:173], v149 offset:1024
	ds_read_b128 v[174:177], v149 offset:2048
	ds_read_b128 v[178:181], v149 offset:3072
	s_mov_b32 m0, s47
	s_nop 0
	global_load_lds_dwordx4 v[224:225], off
	s_mov_b32 m0, s48
	s_nop 0
	global_load_lds_dwordx4 v[226:227], off
	s_add_u32 s34, s34, s40
	s_addc_u32 s35, s35, 0
	s_mov_b32 m0, s49
	v_lshl_add_u64 v[228:229], s[34:35], 0, v[136:137]
	ds_read_b128 v[182:185], v148 offset:32768
	ds_read_b128 v[186:189], v148 offset:33792
	ds_read_b128 v[190:193], v148 offset:34816
	ds_read_b128 v[194:197], v148 offset:35840
	ds_read_b128 v[198:201], v148 offset:36864
	ds_read_b128 v[202:205], v148 offset:37888
	ds_read_b128 v[206:209], v148 offset:38912
	ds_read_b128 v[210:213], v148 offset:39936
	global_load_lds_dwordx4 v[228:229], off
	v_lshl_add_u64 v[228:229], s[34:35], 0, v[132:133]
	s_mov_b32 m0, s50
	s_nop 0
	global_load_lds_dwordx4 v[228:229], off
	s_waitcnt vmcnt(8)
	s_waitcnt lgkmcnt(0)
	s_barrier
	s_setprio 1
	s_waitcnt lgkmcnt(0)
	v_mfma_f32_16x16x32_bf16 v[128:131], v[150:153], v[182:185], v[128:131]
	v_mfma_f32_16x16x32_bf16 v[124:127], v[158:161], v[182:185], v[124:127]
	v_mfma_f32_16x16x32_bf16 v[120:123], v[150:153], v[190:193], v[120:123]
	v_mfma_f32_16x16x32_bf16 v[116:119], v[158:161], v[190:193], v[116:119]
	v_mfma_f32_16x16x32_bf16 v[112:115], v[150:153], v[198:201], v[112:115]
	v_mfma_f32_16x16x32_bf16 v[108:111], v[158:161], v[198:201], v[108:111]
	v_mfma_f32_16x16x32_bf16 v[104:107], v[150:153], v[206:209], v[104:107]
	v_mfma_f32_16x16x32_bf16 v[100:103], v[158:161], v[206:209], v[100:103]
	v_mfma_f32_16x16x32_bf16 v[128:131], v[154:157], v[186:189], v[128:131]
	v_mfma_f32_16x16x32_bf16 v[124:127], v[162:165], v[186:189], v[124:127]
	v_mfma_f32_16x16x32_bf16 v[120:123], v[154:157], v[194:197], v[120:123]
	v_mfma_f32_16x16x32_bf16 v[116:119], v[162:165], v[194:197], v[116:119]
	v_mfma_f32_16x16x32_bf16 v[112:115], v[154:157], v[202:205], v[112:115]
	v_mfma_f32_16x16x32_bf16 v[108:111], v[162:165], v[202:205], v[108:111]
	v_mfma_f32_16x16x32_bf16 v[104:107], v[154:157], v[210:213], v[104:107]
	v_mfma_f32_16x16x32_bf16 v[100:103], v[162:165], v[210:213], v[100:103]
	v_mfma_f32_16x16x32_bf16 v[64:67], v[166:169], v[182:185], v[64:67]
	v_mfma_f32_16x16x32_bf16 v[60:63], v[174:177], v[182:185], v[60:63]
	v_mfma_f32_16x16x32_bf16 v[56:59], v[166:169], v[190:193], v[56:59]
	v_mfma_f32_16x16x32_bf16 v[52:55], v[174:177], v[190:193], v[52:55]
	v_mfma_f32_16x16x32_bf16 v[48:51], v[166:169], v[198:201], v[48:51]
	v_mfma_f32_16x16x32_bf16 v[44:47], v[174:177], v[198:201], v[44:47]
	v_mfma_f32_16x16x32_bf16 v[40:43], v[166:169], v[206:209], v[40:43]
	v_mfma_f32_16x16x32_bf16 v[36:39], v[174:177], v[206:209], v[36:39]
	v_mfma_f32_16x16x32_bf16 v[64:67], v[170:173], v[186:189], v[64:67]
	v_mfma_f32_16x16x32_bf16 v[60:63], v[178:181], v[186:189], v[60:63]
	v_mfma_f32_16x16x32_bf16 v[56:59], v[170:173], v[194:197], v[56:59]
	v_mfma_f32_16x16x32_bf16 v[52:55], v[178:181], v[194:197], v[52:55]
	v_mfma_f32_16x16x32_bf16 v[48:51], v[170:173], v[202:205], v[48:51]
	v_mfma_f32_16x16x32_bf16 v[44:47], v[178:181], v[202:205], v[44:47]
	v_mfma_f32_16x16x32_bf16 v[40:43], v[170:173], v[210:213], v[40:43]
	v_mfma_f32_16x16x32_bf16 v[36:39], v[178:181], v[210:213], v[36:39]
	s_setprio 0
	s_barrier
	s_add_i32 s34, s59, s42
	v_lshl_add_u64 v[214:215], v[214:215], 0, s[84:85]
	s_mov_b32 m0, s34
	ds_read_b128 v[182:185], v148 offset:49152
	ds_read_b128 v[186:189], v148 offset:50176
	ds_read_b128 v[190:193], v148 offset:51200
	ds_read_b128 v[194:197], v148 offset:52224
	ds_read_b128 v[198:201], v148 offset:53248
	ds_read_b128 v[202:205], v148 offset:54272
	ds_read_b128 v[206:209], v148 offset:55296
	ds_read_b128 v[210:213], v148 offset:56320
	global_load_lds_dwordx4 v[214:215], off
	v_lshl_add_u64 v[214:215], v[216:217], 0, s[84:85]
	s_add_i32 m0, s34, 0x2000
	s_add_i32 s34, s60, s42
	global_load_lds_dwordx4 v[214:215], off
	v_lshl_add_u64 v[214:215], v[218:219], 0, s[84:85]
	s_mov_b32 m0, s34
	s_nop 0
	global_load_lds_dwordx4 v[214:215], off
	v_lshl_add_u64 v[214:215], v[220:221], 0, s[84:85]
	s_add_i32 m0, s34, 0x2000
	s_nop 0
	global_load_lds_dwordx4 v[214:215], off
	v_lshl_add_u64 v[214:215], v[224:225], 0, s[84:85]
	s_mov_b32 m0, s52
	s_nop 0
	global_load_lds_dwordx4 v[214:215], off
	v_lshl_add_u64 v[214:215], v[226:227], 0, s[84:85]
	s_mov_b32 m0, s53
	s_nop 0
	global_load_lds_dwordx4 v[214:215], off
	s_waitcnt vmcnt(8)
	s_waitcnt lgkmcnt(0)
	s_barrier
	s_setprio 1
	s_waitcnt lgkmcnt(0)
	v_mfma_f32_16x16x32_bf16 v[96:99], v[150:153], v[182:185], v[96:99]
	v_mfma_f32_16x16x32_bf16 v[92:95], v[158:161], v[182:185], v[92:95]
	v_mfma_f32_16x16x32_bf16 v[88:91], v[150:153], v[190:193], v[88:91]
	v_mfma_f32_16x16x32_bf16 v[84:87], v[158:161], v[190:193], v[84:87]
	v_mfma_f32_16x16x32_bf16 v[80:83], v[150:153], v[198:201], v[80:83]
	v_mfma_f32_16x16x32_bf16 v[76:79], v[158:161], v[198:201], v[76:79]
	v_mfma_f32_16x16x32_bf16 v[72:75], v[150:153], v[206:209], v[72:75]
	v_mfma_f32_16x16x32_bf16 v[68:71], v[158:161], v[206:209], v[68:71]
	v_mfma_f32_16x16x32_bf16 v[96:99], v[154:157], v[186:189], v[96:99]
	v_mfma_f32_16x16x32_bf16 v[92:95], v[162:165], v[186:189], v[92:95]
	v_mfma_f32_16x16x32_bf16 v[88:91], v[154:157], v[194:197], v[88:91]
	v_mfma_f32_16x16x32_bf16 v[84:87], v[162:165], v[194:197], v[84:87]
	v_mfma_f32_16x16x32_bf16 v[80:83], v[154:157], v[202:205], v[80:83]
	v_mfma_f32_16x16x32_bf16 v[76:79], v[162:165], v[202:205], v[76:79]
	v_mfma_f32_16x16x32_bf16 v[72:75], v[154:157], v[210:213], v[72:75]
	v_mfma_f32_16x16x32_bf16 v[68:71], v[162:165], v[210:213], v[68:71]
	v_mfma_f32_16x16x32_bf16 v[32:35], v[166:169], v[182:185], v[32:35]
	v_mfma_f32_16x16x32_bf16 v[28:31], v[174:177], v[182:185], v[28:31]
	v_mfma_f32_16x16x32_bf16 v[24:27], v[166:169], v[190:193], v[24:27]
	v_mfma_f32_16x16x32_bf16 v[20:23], v[174:177], v[190:193], v[20:23]
	v_mfma_f32_16x16x32_bf16 v[16:19], v[166:169], v[198:201], v[16:19]
	v_mfma_f32_16x16x32_bf16 v[12:15], v[174:177], v[198:201], v[12:15]
	v_mfma_f32_16x16x32_bf16 v[8:11], v[166:169], v[206:209], v[8:11]
	v_mfma_f32_16x16x32_bf16 v[4:7], v[174:177], v[206:209], v[4:7]
	v_mfma_f32_16x16x32_bf16 v[32:35], v[170:173], v[186:189], v[32:35]
	v_mfma_f32_16x16x32_bf16 v[28:31], v[178:181], v[186:189], v[28:31]
	v_mfma_f32_16x16x32_bf16 v[24:27], v[170:173], v[194:197], v[24:27]
	v_mfma_f32_16x16x32_bf16 v[20:23], v[178:181], v[194:197], v[20:23]
	v_mfma_f32_16x16x32_bf16 v[16:19], v[170:173], v[202:205], v[16:19]
	v_mfma_f32_16x16x32_bf16 v[12:15], v[178:181], v[202:205], v[12:15]
	v_mfma_f32_16x16x32_bf16 v[8:11], v[170:173], v[210:213], v[8:11]
	v_mfma_f32_16x16x32_bf16 v[4:7], v[178:181], v[210:213], v[4:7]
	s_setprio 0
	s_barrier
	s_add_u32 s30, s30, 0x100
	s_addc_u32 s31, s31, 0
	v_lshl_add_u64 v[144:145], v[144:145], 0, s[86:87]
	v_lshl_add_u64 v[142:143], v[142:143], 0, s[86:87]
	s_cmp_ge_u32 s58, s51
	s_mov_b32 s34, s58
	s_cbranch_scc0 .LBB0_620
	s_and_b64 vcc, exec, s[26:27]
	s_cbranch_vccnz .LBB0_623
	s_and_b64 vcc, exec, s[6:7]
	s_cbranch_vccnz .LBB0_608
	s_branch .LBB0_624
